# SwiGLU epilogue: rs^2 folded into the sigmoid denominator with one packed fma (one packed multiply fewer per output pair)
# speedup vs baseline: 1.0385x; 1.0080x over previous
.LBB0_131:
	v_mul_f32_e32 v136, 0xbfb8aa3b, v165
	v_pk_mul_f32 v[168:169], v[136:137], v[126:127] op_sel_hi:[0,1]
	v_exp_f32_e32 v168, v168
	v_exp_f32_e32 v169, v169
	v_mul_f32_e32 v166, v165, v165
	v_rcp_f32_e32 v166, v166
	v_pk_mul_f32 v[122:123], v[126:127], v[122:123]
	v_pk_mul_f32 v[124:125], v[128:129], v[124:125]
	v_pk_fma_f32 v[168:169], v[168:169], v[166:167], v[166:167] op_sel_hi:[1,0,0]
	s_lshl_b32 s7, s21, 8
	v_rcp_f32_e32 v168, v168
	v_rcp_f32_e32 v169, v169
	s_add_i32 s7, s58, s7
	s_lshl_b32 s9, s20, 2
	s_add_i32 s10, s59, s9
	v_pk_mul_f32 v[122:123], v[168:169], v[122:123]
	v_pk_mul_f32 v[126:127], v[136:137], v[128:129] op_sel_hi:[0,1]
	v_exp_f32_e32 v126, v126
	v_exp_f32_e32 v127, v127
	s_ashr_i32 s38, s7, 4
	s_ashr_i32 s11, s10, 31
	s_ashr_i32 s39, s38, 31
	v_pk_fma_f32 v[126:127], v[126:127], v[166:167], v[166:167] op_sel_hi:[1,0,0]
	s_lshl_b64 s[20:21], s[38:39], 17
	v_rcp_f32_e32 v126, v126
	v_rcp_f32_e32 v127, v127
	s_lshl_b64 s[10:11], s[10:11], 10
	s_add_u32 s9, s33, s20
	s_addc_u32 s13, s96, s21
	v_pk_mul_f32 v[124:125], v[126:127], v[124:125]
	v_pk_mul_f32 v[126:127], v[136:137], v[114:115] op_sel_hi:[0,1]
	v_exp_f32_e32 v126, v126
	v_exp_f32_e32 v127, v127
	v_pk_mul_f32 v[114:115], v[114:115], v[118:119]
	v_mbcnt_lo_u32_b32 v130, -1, 0
	v_mbcnt_hi_u32_b32 v130, -1, v130
	s_add_u32 s20, s9, s10
	v_pk_fma_f32 v[126:127], v[126:127], v[166:167], v[166:167] op_sel_hi:[1,0,0]
	v_lshlrev_b32_e32 v0, 6, v130
	v_rcp_f32_e32 v126, v126
	v_rcp_f32_e32 v127, v127
	v_and_b32_e32 v0, 0x3c0, v0
	v_and_b32_e32 v130, -16, v130
	v_pk_mul_f32 v[120:121], v[116:117], v[120:121]
	v_pk_mul_f32 v[118:119], v[126:127], v[114:115]
	v_pk_mul_f32 v[114:115], v[136:137], v[116:117] op_sel_hi:[0,1]
	v_exp_f32_e32 v114, v114
	v_exp_f32_e32 v115, v115
	s_addc_u32 s21, s13, s11
	v_ashrrev_i32_e32 v131, 31, v130
	v_cvt_pk_bf16_f32 v116, v118, v119
	v_pk_fma_f32 v[114:115], v[114:115], v[166:167], v[166:167] op_sel_hi:[1,0,0]
	v_lshl_add_u64 v[118:119], s[20:21], 0, v[0:1]
	v_rcp_f32_e32 v114, v114
	v_rcp_f32_e32 v115, v115
	v_lshl_add_u64 v[118:119], v[118:119], 0, v[130:131]
	v_pk_mul_f32 v[106:107], v[110:111], v[106:107]
	v_pk_mul_f32 v[108:109], v[112:113], v[108:109]
	v_pk_mul_f32 v[120:121], v[114:115], v[120:121]
	v_cvt_pk_bf16_f32 v114, v122, v123
	v_cvt_pk_bf16_f32 v115, v124, v125
	v_cvt_pk_bf16_f32 v117, v120, v121
	global_store_dwordx4 v[118:119], v[114:117], off
	s_or_b32 s20, s38, 1
	s_ashr_i32 s21, s20, 31
	v_mul_f32_e32 v114, 0xbfb8aa3b, v164
	v_pk_mul_f32 v[118:119], v[114:115], v[110:111] op_sel_hi:[0,1]
	v_exp_f32_e32 v118, v118
	v_exp_f32_e32 v119, v119
	v_mul_f32_e32 v116, v164, v164
	v_rcp_f32_e32 v116, v116
	s_lshl_b64 s[20:21], s[20:21], 17
	s_add_u32 s9, s33, s20
	v_pk_fma_f32 v[118:119], v[118:119], v[116:117], v[116:117] op_sel_hi:[1,0,0]
	s_addc_u32 s13, s96, s21
	v_rcp_f32_e32 v118, v118
	v_rcp_f32_e32 v119, v119
	s_add_u32 s20, s9, s10
	v_pk_mul_f32 v[104:105], v[100:101], v[104:105]
	s_addc_u32 s21, s13, s11
	v_pk_mul_f32 v[106:107], v[118:119], v[106:107]
	v_pk_mul_f32 v[110:111], v[114:115], v[112:113] op_sel_hi:[0,1]
	v_exp_f32_e32 v110, v110
	v_exp_f32_e32 v111, v111
	v_pk_mul_f32 v[90:91], v[94:95], v[90:91]
	v_pk_mul_f32 v[92:93], v[96:97], v[92:93]
	v_pk_mul_f32 v[88:89], v[84:85], v[88:89]
	v_pk_fma_f32 v[110:111], v[110:111], v[116:117], v[116:117] op_sel_hi:[1,0,0]
	v_pk_mul_f32 v[74:75], v[78:79], v[74:75]
	v_rcp_f32_e32 v110, v110
	v_rcp_f32_e32 v111, v111
	v_pk_mul_f32 v[76:77], v[80:81], v[76:77]
	v_pk_mul_f32 v[72:73], v[68:69], v[72:73]
	v_pk_mul_f32 v[58:59], v[62:63], v[58:59]
	v_pk_mul_f32 v[108:109], v[110:111], v[108:109]
	v_pk_mul_f32 v[110:111], v[114:115], v[98:99] op_sel_hi:[0,1]
	v_exp_f32_e32 v110, v110
	v_exp_f32_e32 v111, v111
	v_pk_mul_f32 v[98:99], v[98:99], v[102:103]
	v_pk_mul_f32 v[60:61], v[64:65], v[60:61]
	v_pk_mul_f32 v[56:57], v[52:53], v[56:57]
	v_pk_fma_f32 v[110:111], v[110:111], v[116:117], v[116:117] op_sel_hi:[1,0,0]
	v_pk_mul_f32 v[42:43], v[46:47], v[42:43]
	v_rcp_f32_e32 v110, v110
	v_rcp_f32_e32 v111, v111
	v_pk_mul_f32 v[44:45], v[48:49], v[44:45]
	v_pk_mul_f32 v[40:41], v[36:37], v[40:41]
	v_pk_mul_f32 v[26:27], v[30:31], v[26:27]
	v_pk_mul_f32 v[102:103], v[110:111], v[98:99]
	v_pk_mul_f32 v[98:99], v[114:115], v[100:101] op_sel_hi:[0,1]
	v_exp_f32_e32 v98, v98
	v_exp_f32_e32 v99, v99
	v_cvt_pk_bf16_f32 v100, v102, v103
	v_lshl_add_u64 v[102:103], s[20:21], 0, v[0:1]
	v_lshl_add_u64 v[102:103], v[102:103], 0, v[130:131]
	v_pk_fma_f32 v[98:99], v[98:99], v[116:117], v[116:117] op_sel_hi:[1,0,0]
	s_or_b32 s20, s38, 2
	v_rcp_f32_e32 v98, v98
	v_rcp_f32_e32 v99, v99
	s_ashr_i32 s21, s20, 31
	s_lshl_b64 s[20:21], s[20:21], 17
	s_add_u32 s9, s33, s20
	v_pk_mul_f32 v[104:105], v[98:99], v[104:105]
	v_cvt_pk_bf16_f32 v98, v106, v107
	v_cvt_pk_bf16_f32 v99, v108, v109
	v_cvt_pk_bf16_f32 v101, v104, v105
	global_store_dwordx4 v[102:103], v[98:101], off
	s_addc_u32 s13, s96, s21
	s_add_u32 s20, s9, s10
	v_mul_f32_e32 v98, 0xbfb8aa3b, v163
	v_pk_mul_f32 v[102:103], v[98:99], v[94:95] op_sel_hi:[0,1]
	v_exp_f32_e32 v102, v102
	v_exp_f32_e32 v103, v103
	v_mul_f32_e32 v100, v163, v163
	v_rcp_f32_e32 v100, v100
	s_addc_u32 s21, s13, s11
	v_pk_mul_f32 v[28:29], v[32:33], v[28:29]
	v_pk_fma_f32 v[102:103], v[102:103], v[100:101], v[100:101] op_sel_hi:[1,0,0]
	v_pk_mul_f32 v[24:25], v[20:21], v[24:25]
	v_rcp_f32_e32 v102, v102
	v_rcp_f32_e32 v103, v103
	v_pk_mul_f32 v[10:11], v[14:15], v[10:11]
	v_pk_mul_f32 v[12:13], v[16:17], v[12:13]
	v_pk_mul_f32 v[2:3], v[6:7], v[2:3]
	v_pk_mul_f32 v[90:91], v[102:103], v[90:91]
	v_pk_mul_f32 v[94:95], v[98:99], v[96:97] op_sel_hi:[0,1]
	v_exp_f32_e32 v94, v94
	v_exp_f32_e32 v95, v95
	v_pk_mul_f32 v[4:5], v[8:9], v[4:5]
	v_pk_fma_f32 v[94:95], v[94:95], v[100:101], v[100:101] op_sel_hi:[1,0,0]
	s_nop 0
	v_rcp_f32_e32 v94, v94
	v_rcp_f32_e32 v95, v95
	s_nop 0
	v_pk_mul_f32 v[92:93], v[94:95], v[92:93]
	v_pk_mul_f32 v[94:95], v[98:99], v[82:83] op_sel_hi:[0,1]
	v_exp_f32_e32 v94, v94
	v_exp_f32_e32 v95, v95
	v_pk_mul_f32 v[82:83], v[82:83], v[86:87]
	v_pk_fma_f32 v[94:95], v[94:95], v[100:101], v[100:101] op_sel_hi:[1,0,0]
	s_nop 0
	v_rcp_f32_e32 v94, v94
	v_rcp_f32_e32 v95, v95
	s_nop 0
	v_pk_mul_f32 v[86:87], v[94:95], v[82:83]
	v_pk_mul_f32 v[82:83], v[98:99], v[84:85] op_sel_hi:[0,1]
	v_exp_f32_e32 v82, v82
	v_exp_f32_e32 v83, v83
	v_cvt_pk_bf16_f32 v84, v86, v87
	v_lshl_add_u64 v[86:87], s[20:21], 0, v[0:1]
	v_lshl_add_u64 v[86:87], v[86:87], 0, v[130:131]
	v_pk_fma_f32 v[82:83], v[82:83], v[100:101], v[100:101] op_sel_hi:[1,0,0]
	s_or_b32 s20, s38, 3
	v_rcp_f32_e32 v82, v82
	v_rcp_f32_e32 v83, v83
	s_ashr_i32 s21, s20, 31
	s_lshl_b64 s[20:21], s[20:21], 17
	s_add_u32 s9, s33, s20
	v_pk_mul_f32 v[88:89], v[82:83], v[88:89]
	v_cvt_pk_bf16_f32 v82, v90, v91
	v_cvt_pk_bf16_f32 v83, v92, v93
	v_cvt_pk_bf16_f32 v85, v88, v89
	global_store_dwordx4 v[86:87], v[82:85], off
	s_addc_u32 s13, s96, s21
	s_add_u32 s20, s9, s10
	v_mul_f32_e32 v82, 0xbfb8aa3b, v162
	v_pk_mul_f32 v[86:87], v[82:83], v[78:79] op_sel_hi:[0,1]
	v_exp_f32_e32 v86, v86
	v_exp_f32_e32 v87, v87
	v_mul_f32_e32 v84, v162, v162
	v_rcp_f32_e32 v84, v84
	s_addc_u32 s21, s13, s11
	s_add_i32 s9, s7, 0x80
	v_pk_fma_f32 v[86:87], v[86:87], v[84:85], v[84:85] op_sel_hi:[1,0,0]
	s_nop 0
	v_rcp_f32_e32 v86, v86
	v_rcp_f32_e32 v87, v87
	s_nop 0
	v_pk_mul_f32 v[74:75], v[86:87], v[74:75]
	v_pk_mul_f32 v[78:79], v[82:83], v[80:81] op_sel_hi:[0,1]
	v_exp_f32_e32 v78, v78
	v_exp_f32_e32 v79, v79
	s_nop 0
	v_pk_fma_f32 v[78:79], v[78:79], v[84:85], v[84:85] op_sel_hi:[1,0,0]
	s_nop 0
	v_rcp_f32_e32 v78, v78
	v_rcp_f32_e32 v79, v79
	s_nop 0
	v_pk_mul_f32 v[76:77], v[78:79], v[76:77]
	v_pk_mul_f32 v[78:79], v[82:83], v[66:67] op_sel_hi:[0,1]
	v_exp_f32_e32 v78, v78
	v_exp_f32_e32 v79, v79
	v_pk_mul_f32 v[66:67], v[66:67], v[70:71]
	v_pk_fma_f32 v[78:79], v[78:79], v[84:85], v[84:85] op_sel_hi:[1,0,0]
	s_nop 0
	v_rcp_f32_e32 v78, v78
	v_rcp_f32_e32 v79, v79
	s_nop 0
	v_pk_mul_f32 v[70:71], v[78:79], v[66:67]
	v_pk_mul_f32 v[66:67], v[82:83], v[68:69] op_sel_hi:[0,1]
	v_exp_f32_e32 v66, v66
	v_exp_f32_e32 v67, v67
	v_cvt_pk_bf16_f32 v68, v70, v71
	v_lshl_add_u64 v[70:71], s[20:21], 0, v[0:1]
	v_lshl_add_u64 v[70:71], v[70:71], 0, v[130:131]
	v_pk_fma_f32 v[66:67], v[66:67], v[84:85], v[84:85] op_sel_hi:[1,0,0]
	s_ashr_i32 s20, s9, 4
	v_rcp_f32_e32 v66, v66
	v_rcp_f32_e32 v67, v67
	s_ashr_i32 s21, s20, 31
	s_lshl_b64 s[20:21], s[20:21], 17
	s_add_u32 s9, s33, s20
	v_pk_mul_f32 v[72:73], v[66:67], v[72:73]
	v_cvt_pk_bf16_f32 v66, v74, v75
	v_cvt_pk_bf16_f32 v67, v76, v77
	v_cvt_pk_bf16_f32 v69, v72, v73
	global_store_dwordx4 v[70:71], v[66:69], off
	s_addc_u32 s13, s96, s21
	s_add_u32 s20, s9, s10
	v_mul_f32_e32 v66, 0xbfb8aa3b, v161
	v_pk_mul_f32 v[70:71], v[66:67], v[62:63] op_sel_hi:[0,1]
	v_exp_f32_e32 v70, v70
	v_exp_f32_e32 v71, v71
	v_mul_f32_e32 v68, v161, v161
	v_rcp_f32_e32 v68, v68
	s_addc_u32 s21, s13, s11
	s_add_i32 s9, s7, 0x90
	v_pk_fma_f32 v[70:71], v[70:71], v[68:69], v[68:69] op_sel_hi:[1,0,0]
	s_nop 0
	v_rcp_f32_e32 v70, v70
	v_rcp_f32_e32 v71, v71
	s_nop 0
	v_pk_mul_f32 v[58:59], v[70:71], v[58:59]
	v_pk_mul_f32 v[62:63], v[66:67], v[64:65] op_sel_hi:[0,1]
	v_exp_f32_e32 v62, v62
	v_exp_f32_e32 v63, v63
	s_nop 0
	v_pk_fma_f32 v[62:63], v[62:63], v[68:69], v[68:69] op_sel_hi:[1,0,0]
	s_nop 0
	v_rcp_f32_e32 v62, v62
	v_rcp_f32_e32 v63, v63
	s_nop 0
	v_pk_mul_f32 v[60:61], v[62:63], v[60:61]
	v_pk_mul_f32 v[62:63], v[66:67], v[50:51] op_sel_hi:[0,1]
	v_exp_f32_e32 v62, v62
	v_exp_f32_e32 v63, v63
	v_pk_mul_f32 v[50:51], v[50:51], v[54:55]
	v_pk_fma_f32 v[62:63], v[62:63], v[68:69], v[68:69] op_sel_hi:[1,0,0]
	s_nop 0
	v_rcp_f32_e32 v62, v62
	v_rcp_f32_e32 v63, v63
	s_nop 0
	v_pk_mul_f32 v[54:55], v[62:63], v[50:51]
	v_pk_mul_f32 v[50:51], v[66:67], v[52:53] op_sel_hi:[0,1]
	v_exp_f32_e32 v50, v50
	v_exp_f32_e32 v51, v51
	v_cvt_pk_bf16_f32 v52, v54, v55
	v_lshl_add_u64 v[54:55], s[20:21], 0, v[0:1]
	v_lshl_add_u64 v[54:55], v[54:55], 0, v[130:131]
	v_pk_fma_f32 v[50:51], v[50:51], v[68:69], v[68:69] op_sel_hi:[1,0,0]
	s_ashr_i32 s20, s9, 4
	v_rcp_f32_e32 v50, v50
	v_rcp_f32_e32 v51, v51
	s_ashr_i32 s21, s20, 31
	s_lshl_b64 s[20:21], s[20:21], 17
	s_add_u32 s9, s33, s20
	v_pk_mul_f32 v[56:57], v[50:51], v[56:57]
	v_cvt_pk_bf16_f32 v50, v58, v59
	v_cvt_pk_bf16_f32 v51, v60, v61
	v_cvt_pk_bf16_f32 v53, v56, v57
	global_store_dwordx4 v[54:55], v[50:53], off
	s_addc_u32 s13, s96, s21
	s_add_u32 s20, s9, s10
	v_mul_f32_e32 v50, 0xbfb8aa3b, v160
	v_pk_mul_f32 v[54:55], v[50:51], v[46:47] op_sel_hi:[0,1]
	v_exp_f32_e32 v54, v54
	v_exp_f32_e32 v55, v55
	v_mul_f32_e32 v52, v160, v160
	v_rcp_f32_e32 v52, v52
	s_addc_u32 s21, s13, s11
	s_add_i32 s9, s7, 0xa0
	v_pk_fma_f32 v[54:55], v[54:55], v[52:53], v[52:53] op_sel_hi:[1,0,0]
	s_nop 0
	v_rcp_f32_e32 v54, v54
	v_rcp_f32_e32 v55, v55
	s_nop 0
	v_pk_mul_f32 v[42:43], v[54:55], v[42:43]
	v_pk_mul_f32 v[46:47], v[50:51], v[48:49] op_sel_hi:[0,1]
	v_exp_f32_e32 v46, v46
	v_exp_f32_e32 v47, v47
	s_nop 0
	v_pk_fma_f32 v[46:47], v[46:47], v[52:53], v[52:53] op_sel_hi:[1,0,0]
	s_nop 0
	v_rcp_f32_e32 v46, v46
	v_rcp_f32_e32 v47, v47
	s_nop 0
	v_pk_mul_f32 v[44:45], v[46:47], v[44:45]
	v_pk_mul_f32 v[46:47], v[50:51], v[34:35] op_sel_hi:[0,1]
	v_exp_f32_e32 v46, v46
	v_exp_f32_e32 v47, v47
	v_pk_mul_f32 v[34:35], v[34:35], v[38:39]
	v_pk_fma_f32 v[46:47], v[46:47], v[52:53], v[52:53] op_sel_hi:[1,0,0]
	s_nop 0
	v_rcp_f32_e32 v46, v46
	v_rcp_f32_e32 v47, v47
	s_nop 0
	v_pk_mul_f32 v[38:39], v[46:47], v[34:35]
	v_pk_mul_f32 v[34:35], v[50:51], v[36:37] op_sel_hi:[0,1]
	v_exp_f32_e32 v34, v34
	v_exp_f32_e32 v35, v35
	v_cvt_pk_bf16_f32 v36, v38, v39
	v_lshl_add_u64 v[38:39], s[20:21], 0, v[0:1]
	v_lshl_add_u64 v[38:39], v[38:39], 0, v[130:131]
	v_pk_fma_f32 v[34:35], v[34:35], v[52:53], v[52:53] op_sel_hi:[1,0,0]
	s_ashr_i32 s20, s9, 4
	v_rcp_f32_e32 v34, v34
	v_rcp_f32_e32 v35, v35
	s_ashr_i32 s21, s20, 31
	s_lshl_b64 s[20:21], s[20:21], 17
	s_add_u32 s9, s33, s20
	v_pk_mul_f32 v[40:41], v[34:35], v[40:41]
	v_cvt_pk_bf16_f32 v34, v42, v43
	v_cvt_pk_bf16_f32 v35, v44, v45
	v_cvt_pk_bf16_f32 v37, v40, v41
	global_store_dwordx4 v[38:39], v[34:37], off
	s_addc_u32 s13, s96, s21
	s_add_u32 s20, s9, s10
	v_mul_f32_e32 v34, 0xbfb8aa3b, v154
	v_pk_mul_f32 v[38:39], v[34:35], v[30:31] op_sel_hi:[0,1]
	v_exp_f32_e32 v38, v38
	v_exp_f32_e32 v39, v39
	v_mul_f32_e32 v36, v154, v154
	v_rcp_f32_e32 v36, v36
	s_addc_u32 s21, s13, s11
	s_addk_i32 s7, 0xb0
	v_pk_fma_f32 v[38:39], v[38:39], v[36:37], v[36:37] op_sel_hi:[1,0,0]
	s_nop 0
	v_rcp_f32_e32 v38, v38
	v_rcp_f32_e32 v39, v39
	s_nop 0
	v_pk_mul_f32 v[26:27], v[38:39], v[26:27]
	v_pk_mul_f32 v[30:31], v[34:35], v[32:33] op_sel_hi:[0,1]
	v_exp_f32_e32 v30, v30
	v_exp_f32_e32 v31, v31
	s_nop 0
	v_pk_fma_f32 v[30:31], v[30:31], v[36:37], v[36:37] op_sel_hi:[1,0,0]
	s_nop 0
	v_rcp_f32_e32 v30, v30
	v_rcp_f32_e32 v31, v31
	s_nop 0
	v_pk_mul_f32 v[28:29], v[30:31], v[28:29]
	v_pk_mul_f32 v[30:31], v[34:35], v[18:19] op_sel_hi:[0,1]
	v_exp_f32_e32 v30, v30
	v_exp_f32_e32 v31, v31
	v_pk_mul_f32 v[18:19], v[18:19], v[22:23]
	v_pk_fma_f32 v[30:31], v[30:31], v[36:37], v[36:37] op_sel_hi:[1,0,0]
	s_nop 0
	v_rcp_f32_e32 v30, v30
	v_rcp_f32_e32 v31, v31
	s_nop 0
	v_pk_mul_f32 v[22:23], v[30:31], v[18:19]
	v_pk_mul_f32 v[18:19], v[34:35], v[20:21] op_sel_hi:[0,1]
	v_exp_f32_e32 v18, v18
	v_exp_f32_e32 v19, v19
	v_cvt_pk_bf16_f32 v20, v22, v23
	v_lshl_add_u64 v[22:23], s[20:21], 0, v[0:1]
	v_lshl_add_u64 v[22:23], v[22:23], 0, v[130:131]
	v_pk_fma_f32 v[18:19], v[18:19], v[36:37], v[36:37] op_sel_hi:[1,0,0]
	s_ashr_i32 s20, s7, 4
	v_rcp_f32_e32 v18, v18
	v_rcp_f32_e32 v19, v19
	s_ashr_i32 s21, s20, 31
	s_lshl_b64 s[20:21], s[20:21], 17
	s_add_u32 s7, s33, s20
	v_pk_mul_f32 v[24:25], v[18:19], v[24:25]
	v_cvt_pk_bf16_f32 v18, v26, v27
	v_cvt_pk_bf16_f32 v19, v28, v29
	v_cvt_pk_bf16_f32 v21, v24, v25
	global_store_dwordx4 v[22:23], v[18:21], off
	s_addc_u32 s9, s96, s21
	s_add_u32 s10, s7, s10
	v_mul_f32_e32 v18, 0xbfb8aa3b, v151
	v_pk_mul_f32 v[22:23], v[18:19], v[14:15] op_sel_hi:[0,1]
	v_exp_f32_e32 v22, v22
	v_exp_f32_e32 v23, v23
	v_mul_f32_e32 v20, v151, v151
	v_rcp_f32_e32 v20, v20
	s_addc_u32 s11, s9, s11
	s_and_b64 vcc, exec, s[36:37]
	v_pk_fma_f32 v[22:23], v[22:23], v[20:21], v[20:21] op_sel_hi:[1,0,0]
	s_nop 0
	v_rcp_f32_e32 v22, v22
	v_rcp_f32_e32 v23, v23
	s_nop 0
	v_pk_mul_f32 v[10:11], v[22:23], v[10:11]
	v_pk_mul_f32 v[14:15], v[18:19], v[16:17] op_sel_hi:[0,1]
	v_exp_f32_e32 v14, v14
	v_exp_f32_e32 v15, v15
	s_nop 0
	v_pk_fma_f32 v[14:15], v[14:15], v[20:21], v[20:21] op_sel_hi:[1,0,0]
	s_nop 0
	v_rcp_f32_e32 v14, v14
	v_rcp_f32_e32 v15, v15
	s_nop 0
	v_pk_mul_f32 v[12:13], v[14:15], v[12:13]
	v_pk_mul_f32 v[14:15], v[18:19], v[6:7] op_sel_hi:[0,1]
	v_exp_f32_e32 v14, v14
	v_exp_f32_e32 v15, v15
	s_nop 0
	v_pk_fma_f32 v[14:15], v[14:15], v[20:21], v[20:21] op_sel_hi:[1,0,0]
	s_nop 0
	v_rcp_f32_e32 v14, v14
	v_rcp_f32_e32 v15, v15
	s_nop 0
	v_pk_mul_f32 v[6:7], v[14:15], v[2:3]
	v_pk_mul_f32 v[2:3], v[18:19], v[8:9] op_sel_hi:[0,1]
	v_exp_f32_e32 v2, v2
	v_exp_f32_e32 v3, v3
	s_nop 0
	v_pk_fma_f32 v[2:3], v[2:3], v[20:21], v[20:21] op_sel_hi:[1,0,0]
	s_nop 0
	v_rcp_f32_e32 v2, v2
	v_rcp_f32_e32 v3, v3
	s_nop 0
	v_pk_mul_f32 v[8:9], v[2:3], v[4:5]
	v_cvt_pk_bf16_f32 v4, v6, v7
	v_lshl_add_u64 v[6:7], s[10:11], 0, v[0:1]
	v_cvt_pk_bf16_f32 v2, v10, v11
	v_cvt_pk_bf16_f32 v3, v12, v13
	v_cvt_pk_bf16_f32 v5, v8, v9
	v_lshl_add_u64 v[6:7], v[6:7], 0, v[130:131]
	s_mov_b64 s[10:11], -1
	global_store_dwordx4 v[6:7], v[2:5], off
	s_cbranch_vccnz .LBB0_118
	s_andn2_b64 vcc, exec, s[0:1]
	s_cbranch_vccnz .LBB0_117
	s_barrier
	s_branch .LBB0_117
